# baseline (speedup 1.0000x reference)
.LBB0_321:
	s_add_u32 s44, s60, 0x16800000
	s_addc_u32 s45, s61, 0
	s_add_u32 s2, s60, 0x19800000
	s_addc_u32 s3, s61, 0
	v_writelane_b32 v252, s2, 38
	s_nop 1
	v_writelane_b32 v252, s3, 39
	s_add_u32 s2, s60, 0x1b800000
	s_addc_u32 s3, s61, 0
	v_writelane_b32 v252, s2, 40
	s_cmp_lt_i32 s70, 64
	s_nop 0
	v_writelane_b32 v252, s3, 41
	s_cselect_b64 s[2:3], -1, 0
	s_xor_b64 s[4:5], s[0:1], -1
	s_and_b64 s[2:3], s[2:3], s[4:5]
	s_and_b64 vcc, exec, s[2:3]
	v_writelane_b32 v252, s44, 42
	s_nop 1
	v_writelane_b32 v252, s45, 43
	s_cbranch_vccnz .LBB0_408
	s_sub_i32 s4, s70, 64
	s_and_b64 s[2:3], s[0:1], exec
	s_cselect_b32 s33, s70, s4
	v_mov_b32_e32 v156, v218
	s_cmpk_lt_i32 s33, 0x180
	s_cselect_b64 s[18:19], -1, 0
	s_cmpk_gt_i32 s33, 0x17f
	v_readfirstlane_b32 s3, v156
	s_cbranch_scc1 .LBB0_324
	s_and_b32 s99, s70, 1
	s_mul_i32 s99, s99, 0xc0
	s_add_i32 s99, s99, s33
	s_ashr_i32 s2, s99, 31
	s_lshr_b32 s2, s2, 29
	s_add_i32 s2, s99, s2
	s_and_b32 s4, s2, -8
	s_sub_i32 s4, s99, s4
	s_cmp_lt_i32 s4, 0
	s_cselect_b32 s5, 49, 48
	s_mul_i32 s4, s4, s5
	s_ashr_i32 s2, s2, 3
	s_add_i32 s4, s4, s2
	s_mul_hi_i32 s2, s4, 0x2aaaaaab
	s_lshr_b32 s5, s2, 31
	s_ashr_i32 s2, s2, 3
	s_add_i32 s2, s2, s5
	s_lshl_b32 s5, s2, 3
	s_mul_i32 s2, s2, 48
	s_sub_i32 s2, s4, s2
	s_bfe_i32 s4, s2, 0x80000
	s_bfe_u32 s4, s4, 0x3000c
	s_add_i32 s4, s2, s4
	s_bfe_i32 s6, s4, 0x80000
	s_and_b32 s4, s4, 0xf8
	s_sub_i32 s2, s2, s4
	s_sext_i32_i8 s2, s2
	s_add_i32 s4, s5, s2
	s_sext_i32_i16 s7, s6
	s_ashr_i32 s5, s4, 31
	s_lshr_b32 s6, s7, 3
	s_ashr_i32 s2, s7, 3
	s_lshl_b64 s[20:21], s[4:5], 18
	s_add_u32 s36, s82, s20
	s_addc_u32 s37, s83, s21
	s_bfe_i64 s[6:7], s[6:7], 0x100000
	s_lshl_b64 s[6:7], s[6:7], 18
	s_add_u32 s6, s10, s6
	s_addc_u32 s7, s11, s7
	s_branch .LBB0_325

.LBB0_331:
	s_add_i32 s52, s52, 1
	s_and_b32 s98, s70, 1
	s_add_i32 s98, s98, s52
	s_and_b32 s98, s98, 1
	s_mul_i32 s0, s98, s54
	s_add_i32 s0, s0, s33
	s_cmpk_lt_i32 s52, 2
	s_cselect_b64 s[34:35], -1, 0
	s_cmpk_gt_i32 s52, 1
	s_cbranch_scc1 .LBB0_333
	s_ashr_i32 s1, s0, 31
	s_lshr_b32 s1, s1, 29
	s_add_i32 s1, s0, s1
	s_ashr_i32 s3, s1, 3
	s_and_b32 s1, s1, -8
	s_sub_i32 s0, s0, s1
	s_cmp_lt_i32 s0, 0
	s_cselect_b32 s1, 49, 48
	s_mul_i32 s0, s0, s1
	s_add_i32 s0, s0, s3
	s_mul_hi_i32 s1, s0, 0x2aaaaaab
	s_lshr_b32 s3, s1, 31
	s_ashr_i32 s1, s1, 3
	s_add_i32 s1, s1, s3
	s_lshl_b32 s3, s1, 3
	s_mul_i32 s1, s1, 48
	s_sub_i32 s1, s0, s1
	s_bfe_i32 s0, s1, 0x80000
	s_bfe_u32 s0, s0, 0x3000c
	s_add_i32 s5, s1, s0
	s_bfe_i32 s0, s5, 0x80000
	s_and_b32 s5, s5, 0xf8
	s_sub_i32 s1, s1, s5
	s_sext_i32_i8 s1, s1
	s_sext_i32_i16 s25, s0
	s_add_i32 s24, s3, s1
	s_lshr_b32 s0, s25, 3
	s_ashr_i32 s87, s25, 3
	s_ashr_i32 s25, s24, 31
	s_lshl_b64 s[26:27], s[24:25], 18
	s_add_u32 s26, s82, s26
	s_addc_u32 s27, s83, s27
	s_bfe_i64 s[0:1], s[0:1], 0x100000
	s_lshl_b64 s[0:1], s[0:1], 18
	s_add_u32 s30, s10, s0
	s_addc_u32 s31, s11, s1
